# merge start delay shortened to 2x s_sleep 100 (~6.4us)
# baseline (speedup 1.0000x reference)
; __global__ void __launch_bounds__(NTHREADS, 2) fwd_kernel(Args A) {
;     ...
;         case 4: if (PMASK & 16) { pg8::Gemm g{(const bf16_t*)(ws + WS_Y), wl + WT_BR, Mx, DM, DM, 0, 0}; const bool coop = (ph_hi - ph_lo > 1);
;                   if (last) S.init(NLAT, DM, C.G, C.bid); else if (coop) S.init(NLAT, DM, C.G, C.bid, NCTX, 4); else S.init(MROWS, DM, C.G, C.bid);
;                   pg8::EpiMerge E{(const bf16_t*)(ws + WS_G), (bf16_t*)(ws + WS_MB), (float*)(ws + WS_PB)};
;                   pg8::gemm_phase<pg8::EpiMerge, true>(C.lds, C.tid, g, S, E);
.LBB0_242:
	v_readlane_b32 s100, v249, 56
	s_nop 3
	s_bitcmp1_b32 s100, 3
	s_cbranch_scc0 .Lmerge_nodelay
	s_sleep 100
	s_sleep 100
